# combo28 + dn_prep step 3 KK^T tiles: G/beta rows read once per item (two b128) instead of per (tile, jj) block
# baseline (speedup 1.0000x reference)
; #define LAS __attribute__((address_space(3)))
; __device__ __forceinline__ f32x4 mfma16(const bf16x8& a, const bf16x8& b, const f32x4& c) { return __builtin_amdgcn_mfma_f32_16x16x32_bf16(a, b, c, 0, 0, 0); }
; __device__ __forceinline__ void dn_prep(const Params& p, LAS unsigned char* lds) {
;     ...
;                 if (sel == 0) {
;                     if (tj <= ti) {
;                         f32x4 acc = {0.f, 0.f, 0.f, 0.f};
; #pragma unroll
;                         for (int kk = 0; kk < 4; ++kk) { const bf16x8 a = *(const LAS bf16x8*)(Ks + (16 * ti + fr) * 136 + kk * 32 + 8 * fq), bb = *(const LAS bf16x8*)(Ks + (16 * tj + fr) * 136 + kk * 32 + 8 * fq); acc = mfma16(a, bb, acc); }
;                         const int j = 16 * tj + fr; const float Gj = G_s[j];
; #pragma unroll
;                         for (int jj = 0; jj < 4; ++jj) { const int i = 16 * ti + 4 * fq + jj;
;                             As[i * 68 + j] = (i > j) ? beta_s[i] * acc[jj] * __expf(G_s[i] - Gj) : 0.f; }
.LBB0_293:
	s_or_saveexec_b64 s[24:25], s[24:25]
	v_or_b32_e32 v0, v12, v156
	v_mad_u32_u24 v14, v0, s10, v11
	s_waitcnt lgkmcnt(0)
	v_or_b32_e32 v10, v7, v156
	s_xor_b64 exec, exec, s[24:25]
	s_cbranch_execz .LBB0_328
	ds_read_b128 v[0:3], v14 offset:17408
	v_add_u32_e32 v15, v11, v13
	ds_read_b128 v[16:19], v15 offset:17408
	v_cmp_gt_u32_e32 vcc, v10, v12
	ds_read_b128 v[176:179], v14 offset:17472
	ds_read_b128 v[180:183], v15 offset:17472
	ds_read_b128 v[186:189], v14 offset:17536
	ds_read_b128 v[190:193], v15 offset:17536
	ds_read_b128 v[194:197], v14 offset:17600
	ds_read_b128 v[198:201], v15 offset:17600
	v_lshl_add_u32 v202, v10, 2, 0
	v_add_u32_e32 v202, 0x1a400, v202
	ds_read_b128 v[208:211], v202
	ds_read_b128 v[204:207], v202 offset:256
	s_waitcnt lgkmcnt(8)
	v_mfma_f32_16x16x32_bf16 v[0:3], v[0:3], v[16:19], 0
	s_waitcnt lgkmcnt(6)
	v_mfma_f32_16x16x32_bf16 v[0:3], v[176:179], v[180:183], v[0:3]
	s_waitcnt lgkmcnt(4)
	v_mfma_f32_16x16x32_bf16 v[0:3], v[186:189], v[190:193], v[0:3]
	v_lshl_add_u32 v15, v12, 2, 0
	v_add_u32_e32 v15, 0x1a500, v15
	ds_read_b32 v15, v15
	s_waitcnt lgkmcnt(3)
	v_mfma_f32_16x16x32_bf16 v[0:3], v[194:197], v[198:201], v[0:3]
	v_mov_b32_e32 v16, 0
	v_mov_b32_e32 v17, 0
	s_waitcnt lgkmcnt(0)
	s_and_saveexec_b64 s[0:1], vcc
	s_cbranch_execz .LBB0_296
	v_lshl_add_u32 v17, v10, 2, 0
	v_add_u32_e32 v18, 0x1a500, v17
	v_mov_b32_e32 v18, v204
	v_add_u32_e32 v17, 0x1a400, v17
	v_mov_b32_e32 v17, v208
	v_sub_f32_e32 v18, v18, v15
	v_mul_f32_e32 v18, 0x3fb8aa3b, v18
	v_exp_f32_e32 v18, v18
	v_mul_f32_e32 v0, v0, v17
	v_mul_f32_e32 v17, v0, v18
.LBB0_296:
	s_or_b64 exec, exec, s[0:1]
	s_nop 2
	v_lshl_add_u32 v0, v12, 2, s13
	v_mad_u32_u24 v18, v10, s10, v0
	ds_write_b32 v18, v17
	v_cmp_ge_u32_e32 vcc, v10, v12
	v_mov_b32_e32 v17, 0
	s_and_saveexec_b64 s[0:1], vcc
	s_cbranch_execz .LBB0_298
	v_lshl_add_u32 v17, v10, 2, 0
	v_add_u32_e32 v18, 0x1a504, v17
	v_mov_b32_e32 v18, v205
	v_add_u32_e32 v17, 0x1a404, v17
	v_mov_b32_e32 v17, v209
	v_sub_f32_e32 v18, v18, v15
	v_mul_f32_e32 v18, 0x3fb8aa3b, v18
	v_exp_f32_e32 v18, v18
	v_mul_f32_e32 v1, v1, v17
	v_mul_f32_e32 v17, v1, v18
.LBB0_298:
	s_or_b64 exec, exec, s[0:1]
	v_mul_u32_u24_e32 v1, 0x110, v10
	v_add_u32_e32 v0, v1, v0
	v_or_b32_e32 v1, 2, v10
	v_cmp_gt_u32_e32 vcc, v1, v12
	ds_write_b32 v0, v17 offset:272
	s_and_saveexec_b64 s[0:1], vcc
	s_cbranch_execz .LBB0_300
	v_lshl_add_u32 v1, v1, 2, 0
	v_add_u32_e32 v16, 0x1a500, v1
	v_mov_b32_e32 v16, v206
	v_add_u32_e32 v1, 0x1a400, v1
	v_mov_b32_e32 v1, v210
	v_sub_f32_e32 v16, v16, v15
	v_mul_f32_e32 v16, 0x3fb8aa3b, v16
	v_exp_f32_e32 v16, v16
	v_mul_f32_e32 v1, v2, v1
	v_mul_f32_e32 v16, v1, v16
.LBB0_300:
	s_or_b64 exec, exec, s[0:1]
	v_or_b32_e32 v2, 3, v10
	v_cmp_gt_u32_e32 vcc, v2, v12
	v_mov_b32_e32 v1, 0
	ds_write_b32 v0, v16 offset:544
	s_and_saveexec_b64 s[0:1], vcc
	s_cbranch_execz .LBB0_302
	v_lshl_add_u32 v1, v2, 2, 0
	v_add_u32_e32 v2, 0x1a500, v1
	v_mov_b32_e32 v2, v207
	v_add_u32_e32 v1, 0x1a400, v1
	v_mov_b32_e32 v1, v211
	v_sub_f32_e32 v2, v2, v15
	v_mul_f32_e32 v2, 0x3fb8aa3b, v2
	v_exp_f32_e32 v2, v2
	v_mul_f32_e32 v1, v3, v1
	v_mul_f32_e32 v1, v1, v2

; #define LAS __attribute__((address_space(3)))
; __device__ __forceinline__ f32x4 mfma16(const bf16x8& a, const bf16x8& b, const f32x4& c) { return __builtin_amdgcn_mfma_f32_16x16x32_bf16(a, b, c, 0, 0, 0); }
; __device__ __forceinline__ void dn_prep(const Params& p, LAS unsigned char* lds) {
;     ...
;                 if (sel == 0) {
;                     if (tj <= ti) {
;                         f32x4 acc = {0.f, 0.f, 0.f, 0.f};
; #pragma unroll
;                         for (int kk = 0; kk < 4; ++kk) { const bf16x8 a = *(const LAS bf16x8*)(Ks + (16 * ti + fr) * 136 + kk * 32 + 8 * fq), bb = *(const LAS bf16x8*)(Ks + (16 * tj + fr) * 136 + kk * 32 + 8 * fq); acc = mfma16(a, bb, acc); }
;                         const int j = 16 * tj + fr; const float Gj = G_s[j];
; #pragma unroll
;                         for (int jj = 0; jj < 4; ++jj) { const int i = 16 * ti + 4 * fq + jj;
;                             As[i * 68 + j] = (i > j) ? beta_s[i] * acc[jj] * __expf(G_s[i] - Gj) : 0.f; }
.LBB0_304:
	s_mov_b64 s[28:29], exec
	v_readlane_b32 s0, v248, 24
	v_readlane_b32 s1, v248, 25
	s_and_b64 s[0:1], s[28:29], s[0:1]
	s_mov_b64 exec, s[0:1]
	s_cbranch_execz .LBB0_314
	s_waitcnt lgkmcnt(4)
	v_or_b32_e32 v15, 16, v12
	v_mad_u32_u24 v24, v15, s10, v11
	ds_read_b128 v[0:3], v14 offset:17408
	s_waitcnt lgkmcnt(1)
	ds_read_b128 v[16:19], v24 offset:17408
	v_cmp_gt_u32_e32 vcc, v10, v15
	ds_read_b128 v[176:179], v14 offset:17472
	ds_read_b128 v[180:183], v24 offset:17472
	ds_read_b128 v[186:189], v14 offset:17536
	ds_read_b128 v[190:193], v24 offset:17536
	ds_read_b128 v[194:197], v14 offset:17600
	ds_read_b128 v[198:201], v24 offset:17600
	s_waitcnt lgkmcnt(6)
	v_mfma_f32_16x16x32_bf16 v[0:3], v[0:3], v[16:19], 0
	s_waitcnt lgkmcnt(4)
	v_mfma_f32_16x16x32_bf16 v[0:3], v[176:179], v[180:183], v[0:3]
	s_waitcnt lgkmcnt(2)
	v_mfma_f32_16x16x32_bf16 v[0:3], v[186:189], v[190:193], v[0:3]
	s_waitcnt lgkmcnt(0)
	v_mfma_f32_16x16x32_bf16 v[0:3], v[194:197], v[198:201], v[0:3]
	v_lshl_add_u32 v16, v15, 2, 0
	v_add_u32_e32 v16, 0x1a500, v16
	ds_read_b32 v16, v16
	v_mov_b32_e32 v17, 0
	v_mov_b32_e32 v19, 0
	s_waitcnt lgkmcnt(0)
	s_and_saveexec_b64 s[0:1], vcc
	s_cbranch_execz .LBB0_307
	v_lshl_add_u32 v18, v10, 2, 0
	v_add_u32_e32 v19, 0x1a500, v18
	v_mov_b32_e32 v19, v204
	v_add_u32_e32 v18, 0x1a400, v18
	v_mov_b32_e32 v18, v208
	v_sub_f32_e32 v19, v19, v16
	v_mul_f32_e32 v19, 0x3fb8aa3b, v19
	v_exp_f32_e32 v19, v19
	v_mul_f32_e32 v0, v0, v18
	v_mul_f32_e32 v19, v0, v19
.LBB0_307:
	s_or_b64 exec, exec, s[0:1]
	v_mul_u32_u24_e32 v18, 0x110, v10
	v_lshlrev_b32_e32 v0, 2, v15
	v_add3_u32 v20, s13, v18, v0
	ds_write_b32 v20, v19
	v_cmp_ge_u32_e32 vcc, v10, v15
	v_mov_b32_e32 v19, 0
	s_and_saveexec_b64 s[0:1], vcc
	s_cbranch_execz .LBB0_309
	v_lshl_add_u32 v19, v10, 2, 0
	v_add_u32_e32 v20, 0x1a504, v19
	v_mov_b32_e32 v20, v205
	v_add_u32_e32 v19, 0x1a404, v19
	v_mov_b32_e32 v19, v209
	v_sub_f32_e32 v20, v20, v16
	v_mul_f32_e32 v20, 0x3fb8aa3b, v20
	v_exp_f32_e32 v20, v20
	v_mul_f32_e32 v1, v1, v19
	v_mul_f32_e32 v19, v1, v20
.LBB0_309:
	s_or_b64 exec, exec, s[0:1]
	v_add_u32_e32 v1, 0x110, v18
	v_add3_u32 v18, s13, v1, v0
	ds_write_b32 v18, v19
	v_or_b32_e32 v18, 2, v10
	v_cmp_gt_u32_e32 vcc, v18, v15
	s_and_saveexec_b64 s[0:1], vcc
	s_cbranch_execz .LBB0_311
	v_lshl_add_u32 v17, v18, 2, 0
	v_add_u32_e32 v18, 0x1a500, v17
	v_mov_b32_e32 v18, v206
	v_add_u32_e32 v17, 0x1a400, v17
	v_mov_b32_e32 v17, v210
	v_sub_f32_e32 v18, v18, v16
	v_mul_f32_e32 v18, 0x3fb8aa3b, v18
	v_exp_f32_e32 v18, v18
	v_mul_f32_e32 v2, v2, v17
	v_mul_f32_e32 v17, v2, v18
.LBB0_311:
	s_or_b64 exec, exec, s[0:1]
	v_add_u32_e32 v1, 0x110, v1
	v_or_b32_e32 v2, 3, v10
	v_add3_u32 v0, s13, v1, v0
	v_cmp_gt_u32_e32 vcc, v2, v15
	v_mov_b32_e32 v1, 0
	ds_write_b32 v0, v17
	s_and_saveexec_b64 s[0:1], vcc
	s_cbranch_execz .LBB0_313
	v_lshl_add_u32 v1, v2, 2, 0
	v_add_u32_e32 v2, 0x1a500, v1
	v_mov_b32_e32 v2, v207
	v_add_u32_e32 v1, 0x1a400, v1
	v_mov_b32_e32 v1, v211
	v_sub_f32_e32 v2, v2, v16
	v_mul_f32_e32 v2, 0x3fb8aa3b, v2
	v_exp_f32_e32 v2, v2
	v_mul_f32_e32 v1, v3, v1
	v_mul_f32_e32 v1, v1, v2

; #define LAS __attribute__((address_space(3)))
; __device__ __forceinline__ f32x4 mfma16(const bf16x8& a, const bf16x8& b, const f32x4& c) { return __builtin_amdgcn_mfma_f32_16x16x32_bf16(a, b, c, 0, 0, 0); }
; __device__ __forceinline__ void dn_prep(const Params& p, LAS unsigned char* lds) {
;     ...
;                 if (sel == 0) {
;                     if (tj <= ti) {
;                         f32x4 acc = {0.f, 0.f, 0.f, 0.f};
; #pragma unroll
;                         for (int kk = 0; kk < 4; ++kk) { const bf16x8 a = *(const LAS bf16x8*)(Ks + (16 * ti + fr) * 136 + kk * 32 + 8 * fq), bb = *(const LAS bf16x8*)(Ks + (16 * tj + fr) * 136 + kk * 32 + 8 * fq); acc = mfma16(a, bb, acc); }
;                         const int j = 16 * tj + fr; const float Gj = G_s[j];
; #pragma unroll
;                         for (int jj = 0; jj < 4; ++jj) { const int i = 16 * ti + 4 * fq + jj;
;                             As[i * 68 + j] = (i > j) ? beta_s[i] * acc[jj] * __expf(G_s[i] - Gj) : 0.f; }
.LBB0_316:
	s_and_saveexec_b64 s[28:29], s[20:21]
	s_cbranch_execz .LBB0_326
	s_waitcnt lgkmcnt(4)
	v_or_b32_e32 v15, 32, v12
	v_mad_u32_u24 v24, v15, s10, v11
	ds_read_b128 v[0:3], v14 offset:17408
	s_waitcnt lgkmcnt(1)
	ds_read_b128 v[16:19], v24 offset:17408
	v_cmp_gt_u32_e32 vcc, v10, v15
	ds_read_b128 v[176:179], v14 offset:17472
	ds_read_b128 v[180:183], v24 offset:17472
	ds_read_b128 v[186:189], v14 offset:17536
	ds_read_b128 v[190:193], v24 offset:17536
	ds_read_b128 v[194:197], v14 offset:17600
	ds_read_b128 v[198:201], v24 offset:17600
	s_waitcnt lgkmcnt(6)
	v_mfma_f32_16x16x32_bf16 v[0:3], v[0:3], v[16:19], 0
	s_waitcnt lgkmcnt(4)
	v_mfma_f32_16x16x32_bf16 v[0:3], v[176:179], v[180:183], v[0:3]
	s_waitcnt lgkmcnt(2)
	v_mfma_f32_16x16x32_bf16 v[0:3], v[186:189], v[190:193], v[0:3]
	s_waitcnt lgkmcnt(0)
	v_mfma_f32_16x16x32_bf16 v[0:3], v[194:197], v[198:201], v[0:3]
	v_lshl_add_u32 v16, v15, 2, 0
	v_add_u32_e32 v16, 0x1a500, v16
	ds_read_b32 v16, v16
	v_mov_b32_e32 v17, 0
	v_mov_b32_e32 v19, 0
	s_waitcnt lgkmcnt(0)
	s_and_saveexec_b64 s[0:1], vcc
	s_cbranch_execz .LBB0_319
	v_lshl_add_u32 v18, v10, 2, 0
	v_add_u32_e32 v19, 0x1a500, v18
	v_mov_b32_e32 v19, v204
	v_add_u32_e32 v18, 0x1a400, v18
	v_mov_b32_e32 v18, v208
	v_sub_f32_e32 v19, v19, v16
	v_mul_f32_e32 v19, 0x3fb8aa3b, v19
	v_exp_f32_e32 v19, v19
	v_mul_f32_e32 v0, v0, v18
	v_mul_f32_e32 v19, v0, v19
